# GEMM K-loops: removed the s_setprio 0/1 pair between the two 16-MFMA groups of each compute segment and the redundant lgkmcnt(0) after the barrier
# speedup vs baseline: 1.0141x; 1.0141x over previous
; #define PG8_STAGE(bufoff, gbase, voff) do { _Pragma("unroll") for (int _i = 0; _i < 2; ++_i) \
;         __builtin_amdgcn_global_load_lds((const unsigned*)((const char*)(gbase) + (voff)[_i]), (PG8_LAS unsigned*)(lds + (bufoff) + ldsw + _i * 8192), 16, 0, 0); } while (0)
; #define PG8_LDA(dst, b, h) do { _Pragma("unroll") for (int m = 0; m < 4; ++m) _Pragma("unroll") for (int k = 0; k < 2; ++k) dst[m][k] = *(const PG8_LAS bf16x8*)(lds + PG8_SA(b, h) + aoff + m * 2048 + k * 1024); } while (0)
; #define PG8_LDB(dst, b, h) do { _Pragma("unroll") for (int n = 0; n < 2; ++n) _Pragma("unroll") for (int k = 0; k < 2; ++k) dst[n][k] = *(const PG8_LAS bf16x8*)(lds + PG8_SB(b, h) + boff + n * 2048 + k * 1024); } while (0)
; #define PG8_MMA(ai, bj, At, Bt) do { __builtin_amdgcn_s_setprio(1); _Pragma("unroll") for (int m = 0; m < 4; ++m) _Pragma("unroll") for (int n = 0; n < 2; ++n) _Pragma("unroll") for (int k = 0; k < 2; ++k) \
;         acc[ai][bj][m][n] = __builtin_amdgcn_mfma_f32_16x16x32_bf16(Bt[n][k], At[m][k], acc[ai][bj][m][n], 0, 0, 0); __builtin_amdgcn_s_setprio(0); } while (0)
; #define PG8_WAIT_V(n) asm volatile("s_waitcnt vmcnt(" #n ")" ::: "memory")
; #define PG8_WAIT_L(n) asm volatile("s_waitcnt lgkmcnt(" #n ")" ::: "memory")
; #define PG8_BAR __builtin_amdgcn_s_barrier()
; #define PG8_SCHED __builtin_amdgcn_sched_barrier(0)
; template <class Epi, class Sched, bool ALIGN_EPI = false, bool SP2 = false>
; __device__ __forceinline__ void gemm_phase(PG8_LAS unsigned char* lds, const Gemm g, const Sched& S, const Epi& E) {
;     ...
;             PG8_LDB(B0, 0, 0); PG8_LDB(B1, 0, 1); PG8_SCHED; PG8_LDA(At, 0, 0); PG8_STAGE(PG8_SA(1, 1), a1 + hstep, voffA);
;             PG8_WAIT_V(8); PG8_WAIT_L(0); PG8_BAR; PG8_MMA(0, 0, At, B0); PG8_MMA(0, 1, At, B1); PG8_BAR; PG8_SCHED;
;             PG8_LDA(At, 0, 1); PG8_STAGE(PG8_SB(0, 0), b2, voffB); PG8_STAGE(PG8_SB(0, 1), b2 + hstep, voffB); PG8_STAGE(PG8_SA(0, 0), a2, voffA);
.LBB0_417:
	s_add_u32 s0, s40, 0xfff80080
	s_addc_u32 s1, s41, -1
	s_add_i32 s30, 0, 0x10000
	s_cmp_eq_u32 s19, 28
	s_cselect_b32 s5, s7, s1
	s_cselect_b32 s4, s8, s0
	s_cselect_b32 s1, s9, s17
	s_cselect_b32 s0, s14, s15
	s_add_i32 s33, 0, 0x14000
	v_add_u32_e32 v142, s30, v203
	v_add_u32_e32 v158, s33, v203
	ds_read_b128 v[130:133], v142
	ds_read_b128 v[134:137], v142 offset:1024
	ds_read_b128 v[138:141], v142 offset:2048
	ds_read_b128 v[142:145], v142 offset:3072
	ds_read_b128 v[146:149], v158
	ds_read_b128 v[150:153], v158 offset:1024
	ds_read_b128 v[154:157], v158 offset:2048
	ds_read_b128 v[158:161], v158 offset:3072
	v_lshl_add_u64 v[190:191], s[40:41], 0, v[188:189]
	s_add_i32 m0, s67, 0xc000
	ds_read_b128 v[162:165], v209
	ds_read_b128 v[166:169], v209 offset:1024
	ds_read_b128 v[170:173], v209 offset:2048
	ds_read_b128 v[174:177], v209 offset:3072
	ds_read_b128 v[210:213], v209 offset:4096
	ds_read_b128 v[232:235], v209 offset:5120
	ds_read_b128 v[242:245], v209 offset:6144
	ds_read_b128 v[246:249], v209 offset:7168
	global_load_lds_dwordx4 v[190:191], off
	v_lshl_add_u64 v[190:191], s[40:41], 0, v[186:187]
	s_add_i32 m0, s67, 0xe000
	s_nop 0
	global_load_lds_dwordx4 v[190:191], off
	s_waitcnt vmcnt(8)
	s_waitcnt lgkmcnt(0)
	s_barrier
	s_setprio 1
	v_mfma_f32_16x16x32_bf16 v[126:129], v[130:133], v[162:165], v[126:129]
	v_mfma_f32_16x16x32_bf16 v[122:125], v[138:141], v[162:165], v[122:125]
	v_mfma_f32_16x16x32_bf16 v[110:113], v[130:133], v[170:173], v[110:113]
	v_mfma_f32_16x16x32_bf16 v[106:109], v[138:141], v[170:173], v[106:109]
	v_mfma_f32_16x16x32_bf16 v[92:95], v[130:133], v[210:213], v[92:95]
	v_mfma_f32_16x16x32_bf16 v[88:91], v[138:141], v[210:213], v[88:91]
	v_mfma_f32_16x16x32_bf16 v[76:79], v[130:133], v[242:245], v[76:79]
	v_mfma_f32_16x16x32_bf16 v[72:75], v[138:141], v[242:245], v[72:75]
	v_mfma_f32_16x16x32_bf16 v[126:129], v[134:137], v[166:169], v[126:129]
	v_mfma_f32_16x16x32_bf16 v[122:125], v[142:145], v[166:169], v[122:125]
	v_mfma_f32_16x16x32_bf16 v[110:113], v[134:137], v[174:177], v[110:113]
	v_mfma_f32_16x16x32_bf16 v[106:109], v[142:145], v[174:177], v[106:109]
	v_mfma_f32_16x16x32_bf16 v[92:95], v[134:137], v[232:235], v[92:95]
	v_mfma_f32_16x16x32_bf16 v[88:91], v[142:145], v[232:235], v[88:91]
	v_mfma_f32_16x16x32_bf16 v[76:79], v[134:137], v[246:249], v[76:79]
	v_mfma_f32_16x16x32_bf16 v[72:75], v[142:145], v[246:249], v[72:75]
	v_mfma_f32_16x16x32_bf16 v[118:121], v[146:149], v[162:165], v[118:121]
	v_mfma_f32_16x16x32_bf16 v[114:117], v[154:157], v[162:165], v[114:117]
	v_mfma_f32_16x16x32_bf16 v[102:105], v[146:149], v[170:173], v[102:105]
	v_mfma_f32_16x16x32_bf16 v[98:101], v[154:157], v[170:173], v[98:101]
	v_mfma_f32_16x16x32_bf16 v[84:87], v[146:149], v[210:213], v[84:87]
	v_mfma_f32_16x16x32_bf16 v[80:83], v[154:157], v[210:213], v[80:83]
	v_mfma_f32_16x16x32_bf16 v[68:71], v[146:149], v[242:245], v[68:71]
	v_mfma_f32_16x16x32_bf16 v[64:67], v[154:157], v[242:245], v[64:67]
	v_mfma_f32_16x16x32_bf16 v[118:121], v[150:153], v[166:169], v[118:121]
	v_mfma_f32_16x16x32_bf16 v[114:117], v[158:161], v[166:169], v[114:117]
	v_mfma_f32_16x16x32_bf16 v[102:105], v[150:153], v[174:177], v[102:105]
	v_mfma_f32_16x16x32_bf16 v[98:101], v[158:161], v[174:177], v[98:101]
	v_mfma_f32_16x16x32_bf16 v[84:87], v[150:153], v[232:235], v[84:87]
	v_mfma_f32_16x16x32_bf16 v[80:83], v[158:161], v[232:235], v[80:83]
	v_mfma_f32_16x16x32_bf16 v[68:71], v[150:153], v[246:249], v[68:71]
	v_mfma_f32_16x16x32_bf16 v[64:67], v[158:161], v[246:249], v[64:67]
	s_setprio 0
	s_barrier
	s_add_i32 s30, s30, s28
	v_lshl_add_u64 v[190:191], s[0:1], 0, v[96:97]
	s_mov_b32 m0, s30
	ds_read_b128 v[162:165], v209 offset:16384
	ds_read_b128 v[166:169], v209 offset:17408
	ds_read_b128 v[170:173], v209 offset:18432
	ds_read_b128 v[174:177], v209 offset:19456
	ds_read_b128 v[210:213], v209 offset:20480
	ds_read_b128 v[232:235], v209 offset:21504
	ds_read_b128 v[242:245], v209 offset:22528
	ds_read_b128 v[246:249], v209 offset:23552
	global_load_lds_dwordx4 v[190:191], off
	s_add_i32 m0, s30, 0x2000
	s_add_u32 s30, s0, 0x80000
	v_lshl_add_u64 v[204:205], s[0:1], 0, v[178:179]
	s_addc_u32 s31, s1, 0
	s_add_i32 s33, s33, s28
	global_load_lds_dwordx4 v[204:205], off
	v_lshl_add_u64 v[214:215], s[30:31], 0, v[96:97]
	s_mov_b32 m0, s33
	v_lshl_add_u64 v[228:229], s[4:5], 0, v[180:181]
	global_load_lds_dwordx4 v[214:215], off
	v_lshl_add_u64 v[214:215], s[30:31], 0, v[178:179]
	s_add_i32 m0, s33, 0x2000
	s_nop 0
	global_load_lds_dwordx4 v[214:215], off
	v_lshl_add_u64 v[214:215], s[4:5], 0, v[182:183]
	s_mov_b32 m0, s67
	s_nop 0
	global_load_lds_dwordx4 v[214:215], off
	s_mov_b32 m0, s68
	s_nop 0
	global_load_lds_dwordx4 v[228:229], off
	s_waitcnt vmcnt(8)
	s_waitcnt lgkmcnt(0)
	s_barrier
; #define PG8_STAGE(bufoff, gbase, voff) do { _Pragma("unroll") for (int _i = 0; _i < 2; ++_i) \
;         __builtin_amdgcn_global_load_lds((const unsigned*)((const char*)(gbase) + (voff)[_i]), (PG8_LAS unsigned*)(lds + (bufoff) + ldsw + _i * 8192), 16, 0, 0); } while (0)
; #define PG8_LDA(dst, b, h) do { _Pragma("unroll") for (int m = 0; m < 4; ++m) _Pragma("unroll") for (int k = 0; k < 2; ++k) dst[m][k] = *(const PG8_LAS bf16x8*)(lds + PG8_SA(b, h) + aoff + m * 2048 + k * 1024); } while (0)
; #define PG8_LDB(dst, b, h) do { _Pragma("unroll") for (int n = 0; n < 2; ++n) _Pragma("unroll") for (int k = 0; k < 2; ++k) dst[n][k] = *(const PG8_LAS bf16x8*)(lds + PG8_SB(b, h) + boff + n * 2048 + k * 1024); } while (0)
; #define PG8_MMA(ai, bj, At, Bt) do { __builtin_amdgcn_s_setprio(1); _Pragma("unroll") for (int m = 0; m < 4; ++m) _Pragma("unroll") for (int n = 0; n < 2; ++n) _Pragma("unroll") for (int k = 0; k < 2; ++k) \
;         acc[ai][bj][m][n] = __builtin_amdgcn_mfma_f32_16x16x32_bf16(Bt[n][k], At[m][k], acc[ai][bj][m][n], 0, 0, 0); __builtin_amdgcn_s_setprio(0); } while (0)
; #define PG8_WAIT_V(n) asm volatile("s_waitcnt vmcnt(" #n ")" ::: "memory")
; #define PG8_WAIT_L(n) asm volatile("s_waitcnt lgkmcnt(" #n ")" ::: "memory")
; #define PG8_BAR __builtin_amdgcn_s_barrier()
; #define PG8_SCHED __builtin_amdgcn_sched_barrier(0)
; template <class Epi, class Sched, bool ALIGN_EPI = false, bool SP2 = false>
; __device__ __forceinline__ void gemm_phase(PG8_LAS unsigned char* lds, const Gemm g, const Sched& S, const Epi& E) {
;     ...
;             PG8_WAIT_V(8); PG8_WAIT_L(0); PG8_BAR; PG8_MMA(1, 0, At, B0); PG8_MMA(1, 1, At, B1); PG8_BAR; PG8_SCHED;
;             PG8_LDB(B0, 1, 0); PG8_LDB(B1, 1, 1); PG8_SCHED; PG8_LDA(At, 1, 0); PG8_STAGE(PG8_SA(0, 1), a2 + hstep, voffA);
;             PG8_WAIT_V(8); PG8_WAIT_L(0); PG8_BAR; PG8_MMA(0, 0, At, B0); PG8_MMA(0, 1, At, B1); PG8_BAR; PG8_SCHED;
	s_setprio 1
	v_mfma_f32_16x16x32_bf16 v[60:63], v[130:133], v[162:165], v[60:63]
	v_mfma_f32_16x16x32_bf16 v[56:59], v[138:141], v[162:165], v[56:59]
	v_mfma_f32_16x16x32_bf16 v[44:47], v[130:133], v[170:173], v[44:47]
	v_mfma_f32_16x16x32_bf16 v[40:43], v[138:141], v[170:173], v[40:43]
	v_mfma_f32_16x16x32_bf16 v[28:31], v[130:133], v[210:213], v[28:31]
	v_mfma_f32_16x16x32_bf16 v[24:27], v[138:141], v[210:213], v[24:27]
	v_mfma_f32_16x16x32_bf16 v[12:15], v[130:133], v[242:245], v[12:15]
	v_mfma_f32_16x16x32_bf16 v[8:11], v[138:141], v[242:245], v[8:11]
	v_mfma_f32_16x16x32_bf16 v[60:63], v[134:137], v[166:169], v[60:63]
	v_mfma_f32_16x16x32_bf16 v[56:59], v[142:145], v[166:169], v[56:59]
	v_mfma_f32_16x16x32_bf16 v[44:47], v[134:137], v[174:177], v[44:47]
	v_mfma_f32_16x16x32_bf16 v[40:43], v[142:145], v[174:177], v[40:43]
	v_mfma_f32_16x16x32_bf16 v[28:31], v[134:137], v[232:235], v[28:31]
	v_mfma_f32_16x16x32_bf16 v[24:27], v[142:145], v[232:235], v[24:27]
	v_mfma_f32_16x16x32_bf16 v[12:15], v[134:137], v[246:249], v[12:15]
	v_mfma_f32_16x16x32_bf16 v[8:11], v[142:145], v[246:249], v[8:11]
	v_mfma_f32_16x16x32_bf16 v[52:55], v[146:149], v[162:165], v[52:55]
	v_mfma_f32_16x16x32_bf16 v[48:51], v[154:157], v[162:165], v[48:51]
	v_mfma_f32_16x16x32_bf16 v[36:39], v[146:149], v[170:173], v[36:39]
	v_mfma_f32_16x16x32_bf16 v[32:35], v[154:157], v[170:173], v[32:35]
	v_mfma_f32_16x16x32_bf16 v[20:23], v[146:149], v[210:213], v[20:23]
	v_mfma_f32_16x16x32_bf16 v[16:19], v[154:157], v[210:213], v[16:19]
	v_mfma_f32_16x16x32_bf16 v[4:7], v[146:149], v[242:245], v[4:7]
	v_mfma_f32_16x16x32_bf16 v[0:3], v[154:157], v[242:245], v[0:3]
	v_mfma_f32_16x16x32_bf16 v[52:55], v[150:153], v[166:169], v[52:55]
	v_mfma_f32_16x16x32_bf16 v[48:51], v[158:161], v[166:169], v[48:51]
	v_mfma_f32_16x16x32_bf16 v[36:39], v[150:153], v[174:177], v[36:39]
	v_mfma_f32_16x16x32_bf16 v[32:35], v[158:161], v[174:177], v[32:35]
	v_mfma_f32_16x16x32_bf16 v[20:23], v[150:153], v[232:235], v[20:23]
	v_mfma_f32_16x16x32_bf16 v[16:19], v[158:161], v[232:235], v[16:19]
	v_mfma_f32_16x16x32_bf16 v[4:7], v[150:153], v[246:249], v[4:7]
	v_mfma_f32_16x16x32_bf16 v[0:3], v[158:161], v[246:249], v[0:3]
	s_setprio 0
	s_barrier
	s_add_i32 s30, 0, 0x18000
	s_add_i32 s31, 0, 0x1c000
	v_add_u32_e32 v142, s30, v203
	v_add_u32_e32 v158, s31, v203
	ds_read_b128 v[130:133], v142
	ds_read_b128 v[134:137], v142 offset:1024
	ds_read_b128 v[138:141], v142 offset:2048
	ds_read_b128 v[142:145], v142 offset:3072
	ds_read_b128 v[146:149], v158
	ds_read_b128 v[150:153], v158 offset:1024
	ds_read_b128 v[154:157], v158 offset:2048
	ds_read_b128 v[158:161], v158 offset:3072
	s_add_u32 s4, s4, 0x80000
	s_addc_u32 s5, s5, 0
	s_mov_b32 m0, s69
	v_lshl_add_u64 v[230:231], s[4:5], 0, v[182:183]
	ds_read_b128 v[162:165], v209 offset:32768
	ds_read_b128 v[166:169], v209 offset:33792
	ds_read_b128 v[170:173], v209 offset:34816
	ds_read_b128 v[174:177], v209 offset:35840
	ds_read_b128 v[210:213], v209 offset:36864
	ds_read_b128 v[232:235], v209 offset:37888
	ds_read_b128 v[242:245], v209 offset:38912
	ds_read_b128 v[246:249], v209 offset:39936
	global_load_lds_dwordx4 v[230:231], off
	v_lshl_add_u64 v[230:231], s[4:5], 0, v[180:181]
	s_mov_b32 m0, s72
	s_nop 0
	global_load_lds_dwordx4 v[230:231], off
	s_waitcnt vmcnt(8)
	s_waitcnt lgkmcnt(0)
	s_barrier
	s_setprio 1
	v_mfma_f32_16x16x32_bf16 v[126:129], v[130:133], v[162:165], v[126:129]
	v_mfma_f32_16x16x32_bf16 v[122:125], v[138:141], v[162:165], v[122:125]
	v_mfma_f32_16x16x32_bf16 v[110:113], v[130:133], v[170:173], v[110:113]
	v_mfma_f32_16x16x32_bf16 v[106:109], v[138:141], v[170:173], v[106:109]
	v_mfma_f32_16x16x32_bf16 v[92:95], v[130:133], v[210:213], v[92:95]
	v_mfma_f32_16x16x32_bf16 v[88:91], v[138:141], v[210:213], v[88:91]
	v_mfma_f32_16x16x32_bf16 v[76:79], v[130:133], v[242:245], v[76:79]
	v_mfma_f32_16x16x32_bf16 v[72:75], v[138:141], v[242:245], v[72:75]
	v_mfma_f32_16x16x32_bf16 v[126:129], v[134:137], v[166:169], v[126:129]
	v_mfma_f32_16x16x32_bf16 v[122:125], v[142:145], v[166:169], v[122:125]
	v_mfma_f32_16x16x32_bf16 v[110:113], v[134:137], v[174:177], v[110:113]
	v_mfma_f32_16x16x32_bf16 v[106:109], v[142:145], v[174:177], v[106:109]
	v_mfma_f32_16x16x32_bf16 v[92:95], v[134:137], v[232:235], v[92:95]
	v_mfma_f32_16x16x32_bf16 v[88:91], v[142:145], v[232:235], v[88:91]
	v_mfma_f32_16x16x32_bf16 v[76:79], v[134:137], v[246:249], v[76:79]
	v_mfma_f32_16x16x32_bf16 v[72:75], v[142:145], v[246:249], v[72:75]
	v_mfma_f32_16x16x32_bf16 v[118:121], v[146:149], v[162:165], v[118:121]
	v_mfma_f32_16x16x32_bf16 v[114:117], v[154:157], v[162:165], v[114:117]
	v_mfma_f32_16x16x32_bf16 v[102:105], v[146:149], v[170:173], v[102:105]
	v_mfma_f32_16x16x32_bf16 v[98:101], v[154:157], v[170:173], v[98:101]
	v_mfma_f32_16x16x32_bf16 v[84:87], v[146:149], v[210:213], v[84:87]
	v_mfma_f32_16x16x32_bf16 v[80:83], v[154:157], v[210:213], v[80:83]
	v_mfma_f32_16x16x32_bf16 v[68:71], v[146:149], v[242:245], v[68:71]
	v_mfma_f32_16x16x32_bf16 v[64:67], v[154:157], v[242:245], v[64:67]
	v_mfma_f32_16x16x32_bf16 v[118:121], v[150:153], v[166:169], v[118:121]
	v_mfma_f32_16x16x32_bf16 v[114:117], v[158:161], v[166:169], v[114:117]
	v_mfma_f32_16x16x32_bf16 v[102:105], v[150:153], v[174:177], v[102:105]
	v_mfma_f32_16x16x32_bf16 v[98:101], v[158:161], v[174:177], v[98:101]
	v_mfma_f32_16x16x32_bf16 v[84:87], v[150:153], v[232:235], v[84:87]
	v_mfma_f32_16x16x32_bf16 v[80:83], v[158:161], v[232:235], v[80:83]
	v_mfma_f32_16x16x32_bf16 v[68:71], v[150:153], v[246:249], v[68:71]
	v_mfma_f32_16x16x32_bf16 v[64:67], v[158:161], v[246:249], v[64:67]
	s_setprio 0
	s_barrier
; #define PG8_STAGE(bufoff, gbase, voff) do { _Pragma("unroll") for (int _i = 0; _i < 2; ++_i) \
;         __builtin_amdgcn_global_load_lds((const unsigned*)((const char*)(gbase) + (voff)[_i]), (PG8_LAS unsigned*)(lds + (bufoff) + ldsw + _i * 8192), 16, 0, 0); } while (0)
; #define PG8_LDA(dst, b, h) do { _Pragma("unroll") for (int m = 0; m < 4; ++m) _Pragma("unroll") for (int k = 0; k < 2; ++k) dst[m][k] = *(const PG8_LAS bf16x8*)(lds + PG8_SA(b, h) + aoff + m * 2048 + k * 1024); } while (0)
; #define PG8_MMA(ai, bj, At, Bt) do { __builtin_amdgcn_s_setprio(1); _Pragma("unroll") for (int m = 0; m < 4; ++m) _Pragma("unroll") for (int n = 0; n < 2; ++n) _Pragma("unroll") for (int k = 0; k < 2; ++k) \
;         acc[ai][bj][m][n] = __builtin_amdgcn_mfma_f32_16x16x32_bf16(Bt[n][k], At[m][k], acc[ai][bj][m][n], 0, 0, 0); __builtin_amdgcn_s_setprio(0); } while (0)
; #define PG8_WAIT_V(n) asm volatile("s_waitcnt vmcnt(" #n ")" ::: "memory")
; #define PG8_WAIT_L(n) asm volatile("s_waitcnt lgkmcnt(" #n ")" ::: "memory")
; #define PG8_BAR __builtin_amdgcn_s_barrier()
; #define PG8_SCHED __builtin_amdgcn_sched_barrier(0)
; template <class Epi, class Sched, bool ALIGN_EPI = false, bool SP2 = false>
; __device__ __forceinline__ void gemm_phase(PG8_LAS unsigned char* lds, const Gemm g, const Sched& S, const Epi& E) {
;     ...
;         for (int t = 0; t < nt; t += 2) {
;             const bool last = (t == nt - 2);
;             const char* a1 = cA + (size_t)(t + 1) * kstep;
;             const char* a2 = last ? nA : cA + (size_t)(t + 2) * kstep; const char* b2 = last ? nB : cB + (size_t)(t + 2) * kstep;
;     ...
;             PG8_LDA(At, 1, 1); PG8_STAGE(PG8_SB(1, 0), b3, voffB); PG8_STAGE(PG8_SB(1, 1), b3 + hstep, voffB); PG8_STAGE(PG8_SA(1, 0), a3, voffA);
;             PG8_WAIT_V(8); PG8_WAIT_L(0); PG8_BAR; PG8_MMA(1, 0, At, B0); PG8_MMA(1, 1, At, B1); PG8_BAR; PG8_SCHED;
	s_add_i32 s4, s30, s28
	v_lshl_add_u64 v[190:191], v[190:191], 0, s[20:21]
	s_mov_b32 m0, s4
	ds_read_b128 v[162:165], v209 offset:49152
	ds_read_b128 v[166:169], v209 offset:50176
	ds_read_b128 v[170:173], v209 offset:51200
	ds_read_b128 v[174:177], v209 offset:52224
	ds_read_b128 v[210:213], v209 offset:53248
	ds_read_b128 v[232:235], v209 offset:54272
	ds_read_b128 v[242:245], v209 offset:55296
	ds_read_b128 v[246:249], v209 offset:56320
	global_load_lds_dwordx4 v[190:191], off
	s_add_i32 m0, s4, 0x2000
	s_add_u32 s0, s0, 0x80080
	v_lshl_add_u64 v[190:191], v[204:205], 0, s[20:21]
	s_addc_u32 s1, s1, 0
	s_add_i32 s4, s31, s28
	global_load_lds_dwordx4 v[190:191], off
	v_lshl_add_u64 v[190:191], s[0:1], 0, v[96:97]
	s_mov_b32 m0, s4
	s_nop 0
	global_load_lds_dwordx4 v[190:191], off
	v_lshl_add_u64 v[190:191], s[0:1], 0, v[178:179]
	s_add_i32 m0, s4, 0x2000
	s_nop 0
	global_load_lds_dwordx4 v[190:191], off
	v_lshl_add_u64 v[190:191], v[214:215], 0, s[20:21]
	s_mov_b32 m0, s74
	s_nop 0
	global_load_lds_dwordx4 v[190:191], off
	v_lshl_add_u64 v[190:191], v[228:229], 0, s[20:21]
	s_mov_b32 m0, s75
	s_nop 0
	global_load_lds_dwordx4 v[190:191], off
	s_waitcnt vmcnt(8)
	s_waitcnt lgkmcnt(0)
	s_barrier
	s_setprio 1
	v_mfma_f32_16x16x32_bf16 v[60:63], v[130:133], v[162:165], v[60:63]
	v_mfma_f32_16x16x32_bf16 v[56:59], v[138:141], v[162:165], v[56:59]
	v_mfma_f32_16x16x32_bf16 v[44:47], v[130:133], v[170:173], v[44:47]
	v_mfma_f32_16x16x32_bf16 v[40:43], v[138:141], v[170:173], v[40:43]
	v_mfma_f32_16x16x32_bf16 v[28:31], v[130:133], v[210:213], v[28:31]
	v_mfma_f32_16x16x32_bf16 v[24:27], v[138:141], v[210:213], v[24:27]
	v_mfma_f32_16x16x32_bf16 v[12:15], v[130:133], v[242:245], v[12:15]
	v_mfma_f32_16x16x32_bf16 v[8:11], v[138:141], v[242:245], v[8:11]
	v_mfma_f32_16x16x32_bf16 v[60:63], v[134:137], v[166:169], v[60:63]
	v_mfma_f32_16x16x32_bf16 v[56:59], v[142:145], v[166:169], v[56:59]
	v_mfma_f32_16x16x32_bf16 v[44:47], v[134:137], v[174:177], v[44:47]
	v_mfma_f32_16x16x32_bf16 v[40:43], v[142:145], v[174:177], v[40:43]
	v_mfma_f32_16x16x32_bf16 v[28:31], v[134:137], v[232:235], v[28:31]
	v_mfma_f32_16x16x32_bf16 v[24:27], v[142:145], v[232:235], v[24:27]
	v_mfma_f32_16x16x32_bf16 v[12:15], v[134:137], v[246:249], v[12:15]
	v_mfma_f32_16x16x32_bf16 v[8:11], v[142:145], v[246:249], v[8:11]
	v_mfma_f32_16x16x32_bf16 v[52:55], v[146:149], v[162:165], v[52:55]
	v_mfma_f32_16x16x32_bf16 v[48:51], v[154:157], v[162:165], v[48:51]
	v_mfma_f32_16x16x32_bf16 v[36:39], v[146:149], v[170:173], v[36:39]
	v_mfma_f32_16x16x32_bf16 v[32:35], v[154:157], v[170:173], v[32:35]
	v_mfma_f32_16x16x32_bf16 v[20:23], v[146:149], v[210:213], v[20:23]
	v_mfma_f32_16x16x32_bf16 v[16:19], v[154:157], v[210:213], v[16:19]
	v_mfma_f32_16x16x32_bf16 v[4:7], v[146:149], v[242:245], v[4:7]
	v_mfma_f32_16x16x32_bf16 v[0:3], v[154:157], v[242:245], v[0:3]
	v_mfma_f32_16x16x32_bf16 v[52:55], v[150:153], v[166:169], v[52:55]
	v_mfma_f32_16x16x32_bf16 v[48:51], v[158:161], v[166:169], v[48:51]
	v_mfma_f32_16x16x32_bf16 v[36:39], v[150:153], v[174:177], v[36:39]
	v_mfma_f32_16x16x32_bf16 v[32:35], v[158:161], v[174:177], v[32:35]
	v_mfma_f32_16x16x32_bf16 v[20:23], v[150:153], v[232:235], v[20:23]
	v_mfma_f32_16x16x32_bf16 v[16:19], v[158:161], v[232:235], v[16:19]
	v_mfma_f32_16x16x32_bf16 v[4:7], v[150:153], v[246:249], v[4:7]
	v_mfma_f32_16x16x32_bf16 v[0:3], v[158:161], v[246:249], v[0:3]
	s_setprio 0
	s_barrier
	s_add_i32 s19, s19, 2
	s_add_u32 s15, s15, 0x100
	s_addc_u32 s17, s17, 0
	s_add_u32 s40, s40, 0x100
	s_addc_u32 s41, s41, 0
	s_cmp_gt_u32 s19, 29
	s_cbranch_scc0 .LBB0_417
	s_and_b64 vcc, exec, s[34:35]
	s_cbranch_vccz .LBB0_420
	s_barrier

; #define PG8_STAGE(bufoff, gbase, voff) do { _Pragma("unroll") for (int _i = 0; _i < 2; ++_i) \
;         __builtin_amdgcn_global_load_lds((const unsigned*)((const char*)(gbase) + (voff)[_i]), (PG8_LAS unsigned*)(lds + (bufoff) + ldsw + _i * 8192), 16, 0, 0); } while (0)
; #define PG8_LDA(dst, b, h) do { _Pragma("unroll") for (int m = 0; m < 4; ++m) _Pragma("unroll") for (int k = 0; k < 2; ++k) dst[m][k] = *(const PG8_LAS bf16x8*)(lds + PG8_SA(b, h) + aoff + m * 2048 + k * 1024); } while (0)
; #define PG8_LDB(dst, b, h) do { _Pragma("unroll") for (int n = 0; n < 2; ++n) _Pragma("unroll") for (int k = 0; k < 2; ++k) dst[n][k] = *(const PG8_LAS bf16x8*)(lds + PG8_SB(b, h) + boff + n * 2048 + k * 1024); } while (0)
; #define PG8_MMA(ai, bj, At, Bt) do { __builtin_amdgcn_s_setprio(1); _Pragma("unroll") for (int m = 0; m < 4; ++m) _Pragma("unroll") for (int n = 0; n < 2; ++n) _Pragma("unroll") for (int k = 0; k < 2; ++k) \
;         acc[ai][bj][m][n] = __builtin_amdgcn_mfma_f32_16x16x32_bf16(Bt[n][k], At[m][k], acc[ai][bj][m][n], 0, 0, 0); __builtin_amdgcn_s_setprio(0); } while (0)
; #define PG8_WAIT_V(n) asm volatile("s_waitcnt vmcnt(" #n ")" ::: "memory")
; #define PG8_WAIT_L(n) asm volatile("s_waitcnt lgkmcnt(" #n ")" ::: "memory")
; #define PG8_BAR __builtin_amdgcn_s_barrier()
; #define PG8_SCHED __builtin_amdgcn_sched_barrier(0)
; template <class Epi, class Sched, bool ALIGN_EPI = false, bool SP2 = false>
; __device__ __forceinline__ void gemm_phase(PG8_LAS unsigned char* lds, const Gemm g, const Sched& S, const Epi& E) {
;     ...
;             PG8_LDB(B0, 0, 0); PG8_LDB(B1, 0, 1); PG8_SCHED; PG8_LDA(At, 0, 0); PG8_STAGE(PG8_SA(1, 1), a1 + hstep, voffA);
;             PG8_WAIT_V(8); PG8_WAIT_L(0); PG8_BAR; PG8_MMA(0, 0, At, B0); PG8_MMA(0, 1, At, B1); PG8_BAR; PG8_SCHED;
;             PG8_LDA(At, 0, 1); PG8_STAGE(PG8_SB(0, 0), b2, voffB); PG8_STAGE(PG8_SB(0, 1), b2 + hstep, voffB); PG8_STAGE(PG8_SA(0, 0), a2, voffA);
.LBB0_447:
	s_add_i32 s28, s0, 2
	s_add_u32 s30, s66, 0x80
	s_addc_u32 s1, s67, 0
	s_add_i32 s33, 0, 0x10000
	s_cmp_eq_u32 s59, s0
	s_cselect_b32 s1, s43, s1
	s_cselect_b32 s0, s42, s30
	s_cselect_b32 s31, s65, s23
	s_cselect_b32 s30, s64, s17
	s_add_i32 s52, 0, 0x14000
	v_add_u32_e32 v126, s33, v232
	v_add_u32_e32 v158, s52, v232
	ds_read_b128 v[98:101], v126
	ds_read_b128 v[106:109], v126 offset:1024
	ds_read_b128 v[118:121], v126 offset:2048
	ds_read_b128 v[126:129], v126 offset:3072
	ds_read_b128 v[138:141], v158
	ds_read_b128 v[142:145], v158 offset:1024
	ds_read_b128 v[150:153], v158 offset:2048
	ds_read_b128 v[158:161], v158 offset:3072
	v_lshl_add_u64 v[212:213], s[66:67], 0, v[210:211]
	s_add_i32 m0, s4, 0xc000
	ds_read_b128 v[162:165], v234
	ds_read_b128 v[166:169], v234 offset:1024
	ds_read_b128 v[170:173], v234 offset:2048
	ds_read_b128 v[174:177], v234 offset:3072
	ds_read_b128 v[178:181], v234 offset:4096
	ds_read_b128 v[182:185], v234 offset:5120
	ds_read_b128 v[186:189], v234 offset:6144
	ds_read_b128 v[190:193], v234 offset:7168
	global_load_lds_dwordx4 v[212:213], off
	v_lshl_add_u64 v[212:213], s[66:67], 0, v[208:209]
	s_add_i32 m0, s4, 0xe000
	s_nop 0
	global_load_lds_dwordx4 v[212:213], off
	s_waitcnt vmcnt(8)
	s_waitcnt lgkmcnt(0)
	s_barrier
	s_setprio 1
	v_mfma_f32_16x16x32_bf16 v[154:157], v[98:101], v[162:165], v[154:157]
	v_mfma_f32_16x16x32_bf16 v[146:149], v[118:121], v[162:165], v[146:149]
	v_mfma_f32_16x16x32_bf16 v[122:125], v[98:101], v[170:173], v[122:125]
	v_mfma_f32_16x16x32_bf16 v[114:117], v[118:121], v[170:173], v[114:117]
	v_mfma_f32_16x16x32_bf16 v[92:95], v[98:101], v[178:181], v[92:95]
	v_mfma_f32_16x16x32_bf16 v[88:91], v[118:121], v[178:181], v[88:91]
	v_mfma_f32_16x16x32_bf16 v[76:79], v[98:101], v[186:189], v[76:79]
	v_mfma_f32_16x16x32_bf16 v[72:75], v[118:121], v[186:189], v[72:75]
	v_mfma_f32_16x16x32_bf16 v[154:157], v[106:109], v[166:169], v[154:157]
	v_mfma_f32_16x16x32_bf16 v[146:149], v[126:129], v[166:169], v[146:149]
	v_mfma_f32_16x16x32_bf16 v[122:125], v[106:109], v[174:177], v[122:125]
	v_mfma_f32_16x16x32_bf16 v[114:117], v[126:129], v[174:177], v[114:117]
	v_mfma_f32_16x16x32_bf16 v[92:95], v[106:109], v[182:185], v[92:95]
	v_mfma_f32_16x16x32_bf16 v[88:91], v[126:129], v[182:185], v[88:91]
	v_mfma_f32_16x16x32_bf16 v[76:79], v[106:109], v[190:193], v[76:79]
	v_mfma_f32_16x16x32_bf16 v[72:75], v[126:129], v[190:193], v[72:75]
	v_mfma_f32_16x16x32_bf16 v[134:137], v[138:141], v[162:165], v[134:137]
	v_mfma_f32_16x16x32_bf16 v[130:133], v[150:153], v[162:165], v[130:133]
	v_mfma_f32_16x16x32_bf16 v[110:113], v[138:141], v[170:173], v[110:113]
	v_mfma_f32_16x16x32_bf16 v[102:105], v[150:153], v[170:173], v[102:105]
	v_mfma_f32_16x16x32_bf16 v[84:87], v[138:141], v[178:181], v[84:87]
	v_mfma_f32_16x16x32_bf16 v[80:83], v[150:153], v[178:181], v[80:83]
	v_mfma_f32_16x16x32_bf16 v[68:71], v[138:141], v[186:189], v[68:71]
	v_mfma_f32_16x16x32_bf16 v[64:67], v[150:153], v[186:189], v[64:67]
	v_mfma_f32_16x16x32_bf16 v[134:137], v[142:145], v[166:169], v[134:137]
	v_mfma_f32_16x16x32_bf16 v[130:133], v[158:161], v[166:169], v[130:133]
	v_mfma_f32_16x16x32_bf16 v[110:113], v[142:145], v[174:177], v[110:113]
	v_mfma_f32_16x16x32_bf16 v[102:105], v[158:161], v[174:177], v[102:105]
	v_mfma_f32_16x16x32_bf16 v[84:87], v[142:145], v[182:185], v[84:87]
	v_mfma_f32_16x16x32_bf16 v[80:83], v[158:161], v[182:185], v[80:83]
	v_mfma_f32_16x16x32_bf16 v[68:71], v[142:145], v[190:193], v[68:71]
	v_mfma_f32_16x16x32_bf16 v[64:67], v[158:161], v[190:193], v[64:67]
	s_setprio 0
	s_barrier
	s_add_i32 s33, s33, s2
	v_lshl_add_u64 v[212:213], s[30:31], 0, v[96:97]
	s_mov_b32 m0, s33
	ds_read_b128 v[162:165], v234 offset:16384
	ds_read_b128 v[166:169], v234 offset:17408
	ds_read_b128 v[170:173], v234 offset:18432
	ds_read_b128 v[174:177], v234 offset:19456
	ds_read_b128 v[178:181], v234 offset:20480
	ds_read_b128 v[182:185], v234 offset:21504
	ds_read_b128 v[186:189], v234 offset:22528
	ds_read_b128 v[190:193], v234 offset:23552
	global_load_lds_dwordx4 v[212:213], off
	s_add_i32 m0, s33, 0x2000
	v_lshl_add_u64 v[214:215], s[30:31], 0, v[202:203]
	s_add_u32 s30, s30, s22
	s_addc_u32 s31, s31, 0
	s_add_i32 s33, s52, s2
	global_load_lds_dwordx4 v[214:215], off
	v_lshl_add_u64 v[228:229], s[30:31], 0, v[96:97]
	s_mov_b32 m0, s33
	v_lshl_add_u64 v[236:237], s[30:31], 0, v[202:203]
	global_load_lds_dwordx4 v[228:229], off
	s_add_i32 m0, s33, 0x2000
	v_lshl_add_u64 v[242:243], s[0:1], 0, v[206:207]
	global_load_lds_dwordx4 v[236:237], off
	s_mov_b32 m0, s4
	v_lshl_add_u64 v[244:245], s[0:1], 0, v[204:205]
	global_load_lds_dwordx4 v[242:243], off
	s_mov_b32 m0, s5
	s_nop 0
	global_load_lds_dwordx4 v[244:245], off
	s_waitcnt vmcnt(8)
	s_waitcnt lgkmcnt(0)
	s_barrier
; #define PG8_STAGE(bufoff, gbase, voff) do { _Pragma("unroll") for (int _i = 0; _i < 2; ++_i) \
;         __builtin_amdgcn_global_load_lds((const unsigned*)((const char*)(gbase) + (voff)[_i]), (PG8_LAS unsigned*)(lds + (bufoff) + ldsw + _i * 8192), 16, 0, 0); } while (0)
; #define PG8_LDA(dst, b, h) do { _Pragma("unroll") for (int m = 0; m < 4; ++m) _Pragma("unroll") for (int k = 0; k < 2; ++k) dst[m][k] = *(const PG8_LAS bf16x8*)(lds + PG8_SA(b, h) + aoff + m * 2048 + k * 1024); } while (0)
; #define PG8_LDB(dst, b, h) do { _Pragma("unroll") for (int n = 0; n < 2; ++n) _Pragma("unroll") for (int k = 0; k < 2; ++k) dst[n][k] = *(const PG8_LAS bf16x8*)(lds + PG8_SB(b, h) + boff + n * 2048 + k * 1024); } while (0)
; #define PG8_MMA(ai, bj, At, Bt) do { __builtin_amdgcn_s_setprio(1); _Pragma("unroll") for (int m = 0; m < 4; ++m) _Pragma("unroll") for (int n = 0; n < 2; ++n) _Pragma("unroll") for (int k = 0; k < 2; ++k) \
;         acc[ai][bj][m][n] = __builtin_amdgcn_mfma_f32_16x16x32_bf16(Bt[n][k], At[m][k], acc[ai][bj][m][n], 0, 0, 0); __builtin_amdgcn_s_setprio(0); } while (0)
; #define PG8_WAIT_V(n) asm volatile("s_waitcnt vmcnt(" #n ")" ::: "memory")
; #define PG8_WAIT_L(n) asm volatile("s_waitcnt lgkmcnt(" #n ")" ::: "memory")
; #define PG8_BAR __builtin_amdgcn_s_barrier()
; #define PG8_SCHED __builtin_amdgcn_sched_barrier(0)
; template <class Epi, class Sched, bool ALIGN_EPI = false, bool SP2 = false>
; __device__ __forceinline__ void gemm_phase(PG8_LAS unsigned char* lds, const Gemm g, const Sched& S, const Epi& E) {
;     ...
;             PG8_WAIT_V(8); PG8_WAIT_L(0); PG8_BAR; PG8_MMA(1, 0, At, B0); PG8_MMA(1, 1, At, B1); PG8_BAR; PG8_SCHED;
;             PG8_LDB(B0, 1, 0); PG8_LDB(B1, 1, 1); PG8_SCHED; PG8_LDA(At, 1, 0); PG8_STAGE(PG8_SA(0, 1), a2 + hstep, voffA);
;             PG8_WAIT_V(8); PG8_WAIT_L(0); PG8_BAR; PG8_MMA(0, 0, At, B0); PG8_MMA(0, 1, At, B1); PG8_BAR; PG8_SCHED;
	s_setprio 1
	v_mfma_f32_16x16x32_bf16 v[60:63], v[98:101], v[162:165], v[60:63]
	v_mfma_f32_16x16x32_bf16 v[56:59], v[118:121], v[162:165], v[56:59]
	v_mfma_f32_16x16x32_bf16 v[44:47], v[98:101], v[170:173], v[44:47]
	v_mfma_f32_16x16x32_bf16 v[40:43], v[118:121], v[170:173], v[40:43]
	v_mfma_f32_16x16x32_bf16 v[28:31], v[98:101], v[178:181], v[28:31]
	v_mfma_f32_16x16x32_bf16 v[24:27], v[118:121], v[178:181], v[24:27]
	v_mfma_f32_16x16x32_bf16 v[12:15], v[98:101], v[186:189], v[12:15]
	v_mfma_f32_16x16x32_bf16 v[8:11], v[118:121], v[186:189], v[8:11]
	v_mfma_f32_16x16x32_bf16 v[60:63], v[106:109], v[166:169], v[60:63]
	v_mfma_f32_16x16x32_bf16 v[56:59], v[126:129], v[166:169], v[56:59]
	v_mfma_f32_16x16x32_bf16 v[44:47], v[106:109], v[174:177], v[44:47]
	v_mfma_f32_16x16x32_bf16 v[40:43], v[126:129], v[174:177], v[40:43]
	v_mfma_f32_16x16x32_bf16 v[28:31], v[106:109], v[182:185], v[28:31]
	v_mfma_f32_16x16x32_bf16 v[24:27], v[126:129], v[182:185], v[24:27]
	v_mfma_f32_16x16x32_bf16 v[12:15], v[106:109], v[190:193], v[12:15]
	v_mfma_f32_16x16x32_bf16 v[8:11], v[126:129], v[190:193], v[8:11]
	v_mfma_f32_16x16x32_bf16 v[52:55], v[138:141], v[162:165], v[52:55]
	v_mfma_f32_16x16x32_bf16 v[48:51], v[150:153], v[162:165], v[48:51]
	v_mfma_f32_16x16x32_bf16 v[36:39], v[138:141], v[170:173], v[36:39]
	v_mfma_f32_16x16x32_bf16 v[32:35], v[150:153], v[170:173], v[32:35]
	v_mfma_f32_16x16x32_bf16 v[20:23], v[138:141], v[178:181], v[20:23]
	v_mfma_f32_16x16x32_bf16 v[16:19], v[150:153], v[178:181], v[16:19]
	v_mfma_f32_16x16x32_bf16 v[4:7], v[138:141], v[186:189], v[4:7]
	v_mfma_f32_16x16x32_bf16 v[0:3], v[150:153], v[186:189], v[0:3]
	v_mfma_f32_16x16x32_bf16 v[52:55], v[142:145], v[166:169], v[52:55]
	v_mfma_f32_16x16x32_bf16 v[48:51], v[158:161], v[166:169], v[48:51]
	v_mfma_f32_16x16x32_bf16 v[36:39], v[142:145], v[174:177], v[36:39]
	v_mfma_f32_16x16x32_bf16 v[32:35], v[158:161], v[174:177], v[32:35]
	v_mfma_f32_16x16x32_bf16 v[20:23], v[142:145], v[182:185], v[20:23]
	v_mfma_f32_16x16x32_bf16 v[16:19], v[158:161], v[182:185], v[16:19]
	v_mfma_f32_16x16x32_bf16 v[4:7], v[142:145], v[190:193], v[4:7]
	v_mfma_f32_16x16x32_bf16 v[0:3], v[158:161], v[190:193], v[0:3]
	s_setprio 0
	s_barrier
	s_add_i32 s30, 0, 0x18000
	s_add_i32 s31, 0, 0x1c000
	v_add_u32_e32 v126, s30, v232
	v_add_u32_e32 v158, s31, v232
	ds_read_b128 v[98:101], v126
	ds_read_b128 v[106:109], v126 offset:1024
	ds_read_b128 v[118:121], v126 offset:2048
	ds_read_b128 v[126:129], v126 offset:3072
	ds_read_b128 v[138:141], v158
	ds_read_b128 v[142:145], v158 offset:1024
	ds_read_b128 v[150:153], v158 offset:2048
	ds_read_b128 v[158:161], v158 offset:3072
	s_add_u32 s0, s0, s22
	s_addc_u32 s1, s1, 0
	s_mov_b32 m0, s14
	v_lshl_add_u64 v[246:247], s[0:1], 0, v[206:207]
	ds_read_b128 v[162:165], v234 offset:32768
	ds_read_b128 v[166:169], v234 offset:33792
	ds_read_b128 v[170:173], v234 offset:34816
	ds_read_b128 v[174:177], v234 offset:35840
	ds_read_b128 v[178:181], v234 offset:36864
	ds_read_b128 v[182:185], v234 offset:37888
	ds_read_b128 v[186:189], v234 offset:38912
	ds_read_b128 v[190:193], v234 offset:39936
	global_load_lds_dwordx4 v[246:247], off
	v_lshl_add_u64 v[246:247], s[0:1], 0, v[204:205]
	s_mov_b32 m0, s15
	s_nop 0
	global_load_lds_dwordx4 v[246:247], off
	s_waitcnt vmcnt(8)
	s_waitcnt lgkmcnt(0)
	s_barrier
	s_setprio 1
	v_mfma_f32_16x16x32_bf16 v[154:157], v[98:101], v[162:165], v[154:157]
	v_mfma_f32_16x16x32_bf16 v[146:149], v[118:121], v[162:165], v[146:149]
	v_mfma_f32_16x16x32_bf16 v[122:125], v[98:101], v[170:173], v[122:125]
	v_mfma_f32_16x16x32_bf16 v[114:117], v[118:121], v[170:173], v[114:117]
	v_mfma_f32_16x16x32_bf16 v[92:95], v[98:101], v[178:181], v[92:95]
	v_mfma_f32_16x16x32_bf16 v[88:91], v[118:121], v[178:181], v[88:91]
	v_mfma_f32_16x16x32_bf16 v[76:79], v[98:101], v[186:189], v[76:79]
	v_mfma_f32_16x16x32_bf16 v[72:75], v[118:121], v[186:189], v[72:75]
	v_mfma_f32_16x16x32_bf16 v[154:157], v[106:109], v[166:169], v[154:157]
	v_mfma_f32_16x16x32_bf16 v[146:149], v[126:129], v[166:169], v[146:149]
	v_mfma_f32_16x16x32_bf16 v[122:125], v[106:109], v[174:177], v[122:125]
	v_mfma_f32_16x16x32_bf16 v[114:117], v[126:129], v[174:177], v[114:117]
	v_mfma_f32_16x16x32_bf16 v[92:95], v[106:109], v[182:185], v[92:95]
	v_mfma_f32_16x16x32_bf16 v[88:91], v[126:129], v[182:185], v[88:91]
	v_mfma_f32_16x16x32_bf16 v[76:79], v[106:109], v[190:193], v[76:79]
	v_mfma_f32_16x16x32_bf16 v[72:75], v[126:129], v[190:193], v[72:75]
	v_mfma_f32_16x16x32_bf16 v[134:137], v[138:141], v[162:165], v[134:137]
	v_mfma_f32_16x16x32_bf16 v[130:133], v[150:153], v[162:165], v[130:133]
	v_mfma_f32_16x16x32_bf16 v[110:113], v[138:141], v[170:173], v[110:113]
	v_mfma_f32_16x16x32_bf16 v[102:105], v[150:153], v[170:173], v[102:105]
	v_mfma_f32_16x16x32_bf16 v[84:87], v[138:141], v[178:181], v[84:87]
	v_mfma_f32_16x16x32_bf16 v[80:83], v[150:153], v[178:181], v[80:83]
	v_mfma_f32_16x16x32_bf16 v[68:71], v[138:141], v[186:189], v[68:71]
	v_mfma_f32_16x16x32_bf16 v[64:67], v[150:153], v[186:189], v[64:67]
	v_mfma_f32_16x16x32_bf16 v[134:137], v[142:145], v[166:169], v[134:137]
	v_mfma_f32_16x16x32_bf16 v[130:133], v[158:161], v[166:169], v[130:133]
	v_mfma_f32_16x16x32_bf16 v[110:113], v[142:145], v[174:177], v[110:113]
	v_mfma_f32_16x16x32_bf16 v[102:105], v[158:161], v[174:177], v[102:105]
	v_mfma_f32_16x16x32_bf16 v[84:87], v[142:145], v[182:185], v[84:87]
	v_mfma_f32_16x16x32_bf16 v[80:83], v[158:161], v[182:185], v[80:83]
	v_mfma_f32_16x16x32_bf16 v[68:71], v[142:145], v[190:193], v[68:71]
	v_mfma_f32_16x16x32_bf16 v[64:67], v[158:161], v[190:193], v[64:67]
	s_setprio 0
	s_barrier
; #define PG8_STAGE(bufoff, gbase, voff) do { _Pragma("unroll") for (int _i = 0; _i < 2; ++_i) \
;         __builtin_amdgcn_global_load_lds((const unsigned*)((const char*)(gbase) + (voff)[_i]), (PG8_LAS unsigned*)(lds + (bufoff) + ldsw + _i * 8192), 16, 0, 0); } while (0)
; #define PG8_LDA(dst, b, h) do { _Pragma("unroll") for (int m = 0; m < 4; ++m) _Pragma("unroll") for (int k = 0; k < 2; ++k) dst[m][k] = *(const PG8_LAS bf16x8*)(lds + PG8_SA(b, h) + aoff + m * 2048 + k * 1024); } while (0)
; #define PG8_MMA(ai, bj, At, Bt) do { __builtin_amdgcn_s_setprio(1); _Pragma("unroll") for (int m = 0; m < 4; ++m) _Pragma("unroll") for (int n = 0; n < 2; ++n) _Pragma("unroll") for (int k = 0; k < 2; ++k) \
;         acc[ai][bj][m][n] = __builtin_amdgcn_mfma_f32_16x16x32_bf16(Bt[n][k], At[m][k], acc[ai][bj][m][n], 0, 0, 0); __builtin_amdgcn_s_setprio(0); } while (0)
; #define PG8_WAIT_V(n) asm volatile("s_waitcnt vmcnt(" #n ")" ::: "memory")
; #define PG8_WAIT_L(n) asm volatile("s_waitcnt lgkmcnt(" #n ")" ::: "memory")
; #define PG8_BAR __builtin_amdgcn_s_barrier()
; #define PG8_SCHED __builtin_amdgcn_sched_barrier(0)
; template <class Epi, class Sched, bool ALIGN_EPI = false, bool SP2 = false>
; __device__ __forceinline__ void gemm_phase(PG8_LAS unsigned char* lds, const Gemm g, const Sched& S, const Epi& E) {
;     ...
;             PG8_LDA(At, 1, 1); PG8_STAGE(PG8_SB(1, 0), b3, voffB); PG8_STAGE(PG8_SB(1, 1), b3 + hstep, voffB); PG8_STAGE(PG8_SA(1, 0), a3, voffA);
;             PG8_WAIT_V(8); PG8_WAIT_L(0); PG8_BAR; PG8_MMA(1, 0, At, B0); PG8_MMA(1, 1, At, B1); PG8_BAR; PG8_SCHED;
	s_add_i32 s0, s30, s2
	v_lshl_add_u64 v[212:213], v[212:213], 0, s[20:21]
	s_mov_b32 m0, s0
	ds_read_b128 v[162:165], v234 offset:49152
	ds_read_b128 v[166:169], v234 offset:50176
	ds_read_b128 v[170:173], v234 offset:51200
	ds_read_b128 v[174:177], v234 offset:52224
	ds_read_b128 v[178:181], v234 offset:53248
	ds_read_b128 v[182:185], v234 offset:54272
	ds_read_b128 v[186:189], v234 offset:55296
	ds_read_b128 v[190:193], v234 offset:56320
	global_load_lds_dwordx4 v[212:213], off
	v_lshl_add_u64 v[212:213], v[214:215], 0, s[20:21]
	s_add_i32 m0, s0, 0x2000
	s_add_i32 s0, s31, s2
	global_load_lds_dwordx4 v[212:213], off
	v_lshl_add_u64 v[212:213], v[228:229], 0, s[20:21]
	s_mov_b32 m0, s0
	s_nop 0
	global_load_lds_dwordx4 v[212:213], off
	v_lshl_add_u64 v[212:213], v[236:237], 0, s[20:21]
	s_add_i32 m0, s0, 0x2000
	s_nop 0
	global_load_lds_dwordx4 v[212:213], off
	v_lshl_add_u64 v[212:213], v[242:243], 0, s[20:21]
	s_mov_b32 m0, s19
	s_nop 0
	global_load_lds_dwordx4 v[212:213], off
	v_lshl_add_u64 v[212:213], v[244:245], 0, s[20:21]
	s_mov_b32 m0, s46
	s_nop 0
	global_load_lds_dwordx4 v[212:213], off
	s_waitcnt vmcnt(8)
	s_waitcnt lgkmcnt(0)
	s_barrier
	s_setprio 1
	v_mfma_f32_16x16x32_bf16 v[60:63], v[98:101], v[162:165], v[60:63]
	v_mfma_f32_16x16x32_bf16 v[56:59], v[118:121], v[162:165], v[56:59]
	v_mfma_f32_16x16x32_bf16 v[44:47], v[98:101], v[170:173], v[44:47]
	v_mfma_f32_16x16x32_bf16 v[40:43], v[118:121], v[170:173], v[40:43]
	v_mfma_f32_16x16x32_bf16 v[28:31], v[98:101], v[178:181], v[28:31]
	v_mfma_f32_16x16x32_bf16 v[24:27], v[118:121], v[178:181], v[24:27]
	v_mfma_f32_16x16x32_bf16 v[12:15], v[98:101], v[186:189], v[12:15]
	v_mfma_f32_16x16x32_bf16 v[8:11], v[118:121], v[186:189], v[8:11]
	v_mfma_f32_16x16x32_bf16 v[60:63], v[106:109], v[166:169], v[60:63]
	v_mfma_f32_16x16x32_bf16 v[56:59], v[126:129], v[166:169], v[56:59]
	v_mfma_f32_16x16x32_bf16 v[44:47], v[106:109], v[174:177], v[44:47]
	v_mfma_f32_16x16x32_bf16 v[40:43], v[126:129], v[174:177], v[40:43]
	v_mfma_f32_16x16x32_bf16 v[28:31], v[106:109], v[182:185], v[28:31]
	v_mfma_f32_16x16x32_bf16 v[24:27], v[126:129], v[182:185], v[24:27]
	v_mfma_f32_16x16x32_bf16 v[12:15], v[106:109], v[190:193], v[12:15]
	v_mfma_f32_16x16x32_bf16 v[8:11], v[126:129], v[190:193], v[8:11]
	v_mfma_f32_16x16x32_bf16 v[52:55], v[138:141], v[162:165], v[52:55]
	v_mfma_f32_16x16x32_bf16 v[48:51], v[150:153], v[162:165], v[48:51]
	v_mfma_f32_16x16x32_bf16 v[36:39], v[138:141], v[170:173], v[36:39]
	v_mfma_f32_16x16x32_bf16 v[32:35], v[150:153], v[170:173], v[32:35]
	v_mfma_f32_16x16x32_bf16 v[20:23], v[138:141], v[178:181], v[20:23]
	v_mfma_f32_16x16x32_bf16 v[16:19], v[150:153], v[178:181], v[16:19]
	v_mfma_f32_16x16x32_bf16 v[4:7], v[138:141], v[186:189], v[4:7]
	v_mfma_f32_16x16x32_bf16 v[0:3], v[150:153], v[186:189], v[0:3]
	v_mfma_f32_16x16x32_bf16 v[52:55], v[142:145], v[166:169], v[52:55]
	v_mfma_f32_16x16x32_bf16 v[48:51], v[158:161], v[166:169], v[48:51]
	v_mfma_f32_16x16x32_bf16 v[36:39], v[142:145], v[174:177], v[36:39]
	v_mfma_f32_16x16x32_bf16 v[32:35], v[158:161], v[174:177], v[32:35]
	v_mfma_f32_16x16x32_bf16 v[20:23], v[142:145], v[182:185], v[20:23]
	v_mfma_f32_16x16x32_bf16 v[16:19], v[158:161], v[182:185], v[16:19]
	v_mfma_f32_16x16x32_bf16 v[4:7], v[142:145], v[190:193], v[4:7]
	v_mfma_f32_16x16x32_bf16 v[0:3], v[158:161], v[190:193], v[0:3]
	s_setprio 0
	s_barrier
	s_add_u32 s17, s17, 0x100
	s_addc_u32 s23, s23, 0
	s_add_u32 s66, s66, 0x100
	s_addc_u32 s67, s67, 0
	s_cmp_ge_u32 s28, s49
	s_mov_b32 s0, s28
	s_cbranch_scc0 .LBB0_447
	s_and_b64 vcc, exec, s[62:63]
	s_cbranch_vccz .LBB0_450
	s_barrier

; #define PG8_STAGE(bufoff, gbase, voff) do { _Pragma("unroll") for (int _i = 0; _i < 2; ++_i) \
;         __builtin_amdgcn_global_load_lds((const unsigned*)((const char*)(gbase) + (voff)[_i]), (PG8_LAS unsigned*)(lds + (bufoff) + ldsw + _i * 8192), 16, 0, 0); } while (0)
; #define PG8_LDA(dst, b, h) do { _Pragma("unroll") for (int m = 0; m < 4; ++m) _Pragma("unroll") for (int k = 0; k < 2; ++k) dst[m][k] = *(const PG8_LAS bf16x8*)(lds + PG8_SA(b, h) + aoff + m * 2048 + k * 1024); } while (0)
; #define PG8_LDB(dst, b, h) do { _Pragma("unroll") for (int n = 0; n < 2; ++n) _Pragma("unroll") for (int k = 0; k < 2; ++k) dst[n][k] = *(const PG8_LAS bf16x8*)(lds + PG8_SB(b, h) + boff + n * 2048 + k * 1024); } while (0)
; #define PG8_MMA(ai, bj, At, Bt) do { __builtin_amdgcn_s_setprio(1); _Pragma("unroll") for (int m = 0; m < 4; ++m) _Pragma("unroll") for (int n = 0; n < 2; ++n) _Pragma("unroll") for (int k = 0; k < 2; ++k) \
;         acc[ai][bj][m][n] = __builtin_amdgcn_mfma_f32_16x16x32_bf16(Bt[n][k], At[m][k], acc[ai][bj][m][n], 0, 0, 0); __builtin_amdgcn_s_setprio(0); } while (0)
; #define PG8_WAIT_V(n) asm volatile("s_waitcnt vmcnt(" #n ")" ::: "memory")
; #define PG8_WAIT_L(n) asm volatile("s_waitcnt lgkmcnt(" #n ")" ::: "memory")
; template <class Epi, class Sched, bool ALIGN_EPI = false, bool SP2 = false>
; __device__ __forceinline__ void gemm_phase(PG8_LAS unsigned char* lds, const Gemm g, const Sched& S, const Epi& E) {
;     ...
;             const bool last = (t == nt - 2);
;             const char* a1 = cA + (size_t)(t + 1) * kstep;
;             const char* a2 = last ? nA : cA + (size_t)(t + 2) * kstep; const char* b2 = last ? nB : cB + (size_t)(t + 2) * kstep;
;             const char* a3 = a2 + kstep; const char* b3 = b2 + kstep;
;             if (last && has_next) S.a_ready(nxt);
;             if constexpr (SP2) {
;             PG8_LDB(B0, 0, 0); PG8_LDB(B1, 0, 1); PG8_SCHED; PG8_LDA(At, 0, 0); PG8_STAGE(PG8_SA(1, 1), a1 + hstep, voffA);
;             PG8_WAIT_V(8); PG8_WAIT_L(0); PG8_BAR; PG8_MMA(0, 0, At, B0); PG8_MMA(0, 1, At, B1); PG8_BAR; PG8_SCHED;
;             PG8_LDA(At, 0, 1); PG8_STAGE(PG8_SB(0, 0), b2, voffB); PG8_STAGE(PG8_SB(0, 1), b2 + hstep, voffB); PG8_STAGE(PG8_SA(0, 0), a2, voffA);
;             PG8_WAIT_V(8); PG8_WAIT_L(0); PG8_BAR; PG8_MMA(1, 0, At, B0); PG8_MMA(1, 1, At, B1); PG8_BAR; PG8_SCHED;
.LBB0_510:
	s_add_i32 s95, s0, 2
	s_add_u32 s96, s40, 0x80
	s_addc_u32 s1, s41, 0
	s_add_i32 vcc_lo, 0, 0x10000
	s_cmp_eq_u32 s7, s0
	s_cselect_b32 s1, s89, s1
	s_cselect_b32 s0, s88, s96
	s_cselect_b32 s97, s87, s94
	s_cselect_b32 s96, s86, s45
	s_add_i32 vcc_hi, 0, 0x14000
	v_add_u32_e32 v142, vcc_lo, v193
	v_add_u32_e32 v158, vcc_hi, v193
	ds_read_b128 v[130:133], v142
	ds_read_b128 v[134:137], v142 offset:1024
	ds_read_b128 v[138:141], v142 offset:2048
	ds_read_b128 v[142:145], v142 offset:3072
	ds_read_b128 v[146:149], v158
	ds_read_b128 v[150:153], v158 offset:1024
	ds_read_b128 v[154:157], v158 offset:2048
	ds_read_b128 v[158:161], v158 offset:3072
	v_lshl_add_u64 v[202:203], s[40:41], 0, v[188:189]
	s_add_i32 m0, s90, 0xc000
	ds_read_b128 v[162:165], v207
	ds_read_b128 v[166:169], v207 offset:1024
	ds_read_b128 v[170:173], v207 offset:2048
	ds_read_b128 v[174:177], v207 offset:3072
	ds_read_b128 v[208:211], v207 offset:4096
	ds_read_b128 v[212:215], v207 offset:5120
	ds_read_b128 v[232:235], v207 offset:6144
	ds_read_b128 v[242:245], v207 offset:7168
	global_load_lds_dwordx4 v[202:203], off
	v_lshl_add_u64 v[202:203], s[40:41], 0, v[186:187]
	s_add_i32 m0, s90, 0xe000
	s_nop 0
	global_load_lds_dwordx4 v[202:203], off
	s_waitcnt vmcnt(8)
	s_waitcnt lgkmcnt(0)
	s_barrier
	s_setprio 1
	v_mfma_f32_16x16x32_bf16 v[126:129], v[130:133], v[162:165], v[126:129]
	v_mfma_f32_16x16x32_bf16 v[122:125], v[138:141], v[162:165], v[122:125]
	v_mfma_f32_16x16x32_bf16 v[114:117], v[130:133], v[170:173], v[114:117]
	v_mfma_f32_16x16x32_bf16 v[106:109], v[138:141], v[170:173], v[106:109]
	v_mfma_f32_16x16x32_bf16 v[98:101], v[130:133], v[208:211], v[98:101]
	v_mfma_f32_16x16x32_bf16 v[88:91], v[138:141], v[208:211], v[88:91]
	v_mfma_f32_16x16x32_bf16 v[80:83], v[130:133], v[232:235], v[80:83]
	v_mfma_f32_16x16x32_bf16 v[72:75], v[138:141], v[232:235], v[72:75]
	v_mfma_f32_16x16x32_bf16 v[126:129], v[134:137], v[166:169], v[126:129]
	v_mfma_f32_16x16x32_bf16 v[122:125], v[142:145], v[166:169], v[122:125]
	v_mfma_f32_16x16x32_bf16 v[114:117], v[134:137], v[174:177], v[114:117]
	v_mfma_f32_16x16x32_bf16 v[106:109], v[142:145], v[174:177], v[106:109]
	v_mfma_f32_16x16x32_bf16 v[98:101], v[134:137], v[212:215], v[98:101]
	v_mfma_f32_16x16x32_bf16 v[88:91], v[142:145], v[212:215], v[88:91]
	v_mfma_f32_16x16x32_bf16 v[80:83], v[134:137], v[242:245], v[80:83]
	v_mfma_f32_16x16x32_bf16 v[72:75], v[142:145], v[242:245], v[72:75]
	v_mfma_f32_16x16x32_bf16 v[118:121], v[146:149], v[162:165], v[118:121]
	v_mfma_f32_16x16x32_bf16 v[110:113], v[154:157], v[162:165], v[110:113]
	v_mfma_f32_16x16x32_bf16 v[102:105], v[146:149], v[170:173], v[102:105]
	v_mfma_f32_16x16x32_bf16 v[92:95], v[154:157], v[170:173], v[92:95]
	v_mfma_f32_16x16x32_bf16 v[84:87], v[146:149], v[208:211], v[84:87]
	v_mfma_f32_16x16x32_bf16 v[76:79], v[154:157], v[208:211], v[76:79]
	v_mfma_f32_16x16x32_bf16 v[68:71], v[146:149], v[232:235], v[68:71]
	v_mfma_f32_16x16x32_bf16 v[64:67], v[154:157], v[232:235], v[64:67]
	v_mfma_f32_16x16x32_bf16 v[118:121], v[150:153], v[166:169], v[118:121]
	v_mfma_f32_16x16x32_bf16 v[110:113], v[158:161], v[166:169], v[110:113]
	v_mfma_f32_16x16x32_bf16 v[102:105], v[150:153], v[174:177], v[102:105]
	v_mfma_f32_16x16x32_bf16 v[92:95], v[158:161], v[174:177], v[92:95]
	v_mfma_f32_16x16x32_bf16 v[84:87], v[150:153], v[212:215], v[84:87]
	v_mfma_f32_16x16x32_bf16 v[76:79], v[158:161], v[212:215], v[76:79]
	v_mfma_f32_16x16x32_bf16 v[68:71], v[150:153], v[242:245], v[68:71]
	v_mfma_f32_16x16x32_bf16 v[64:67], v[158:161], v[242:245], v[64:67]
	s_setprio 0
	s_barrier
	s_add_i32 vcc_lo, vcc_lo, s4
	v_lshl_add_u64 v[202:203], s[96:97], 0, v[96:97]
	s_mov_b32 m0, vcc_lo
	ds_read_b128 v[162:165], v207 offset:16384
	ds_read_b128 v[166:169], v207 offset:17408
	ds_read_b128 v[170:173], v207 offset:18432
	ds_read_b128 v[174:177], v207 offset:19456
	ds_read_b128 v[208:211], v207 offset:20480
	ds_read_b128 v[212:215], v207 offset:21504
	ds_read_b128 v[232:235], v207 offset:22528
	ds_read_b128 v[242:245], v207 offset:23552
	global_load_lds_dwordx4 v[202:203], off
	s_add_i32 m0, vcc_lo, 0x2000
	v_lshl_add_u64 v[228:229], s[96:97], 0, v[178:179]
	s_add_u32 s96, s96, s28
	s_addc_u32 s97, s97, 0
	s_add_i32 vcc_lo, vcc_hi, s4
	global_load_lds_dwordx4 v[228:229], off
	v_lshl_add_u64 v[230:231], s[96:97], 0, v[96:97]
	s_mov_b32 m0, vcc_lo
	v_lshl_add_u64 v[246:247], s[96:97], 0, v[178:179]
	global_load_lds_dwordx4 v[230:231], off
	s_add_i32 m0, vcc_lo, 0x2000
	v_lshl_add_u64 v[248:249], s[0:1], 0, v[182:183]
	global_load_lds_dwordx4 v[246:247], off
	s_mov_b32 m0, s90
	v_lshl_add_u64 v[236:237], s[0:1], 0, v[180:181]
	global_load_lds_dwordx4 v[248:249], off
	s_mov_b32 m0, s8
	s_nop 0
	global_load_lds_dwordx4 v[236:237], off
	s_waitcnt vmcnt(8)
	s_waitcnt lgkmcnt(0)
	s_barrier
; #define PG8_STAGE(bufoff, gbase, voff) do { _Pragma("unroll") for (int _i = 0; _i < 2; ++_i) \
;         __builtin_amdgcn_global_load_lds((const unsigned*)((const char*)(gbase) + (voff)[_i]), (PG8_LAS unsigned*)(lds + (bufoff) + ldsw + _i * 8192), 16, 0, 0); } while (0)
; #define PG8_LDA(dst, b, h) do { _Pragma("unroll") for (int m = 0; m < 4; ++m) _Pragma("unroll") for (int k = 0; k < 2; ++k) dst[m][k] = *(const PG8_LAS bf16x8*)(lds + PG8_SA(b, h) + aoff + m * 2048 + k * 1024); } while (0)
; #define PG8_LDB(dst, b, h) do { _Pragma("unroll") for (int n = 0; n < 2; ++n) _Pragma("unroll") for (int k = 0; k < 2; ++k) dst[n][k] = *(const PG8_LAS bf16x8*)(lds + PG8_SB(b, h) + boff + n * 2048 + k * 1024); } while (0)
; #define PG8_MMA(ai, bj, At, Bt) do { __builtin_amdgcn_s_setprio(1); _Pragma("unroll") for (int m = 0; m < 4; ++m) _Pragma("unroll") for (int n = 0; n < 2; ++n) _Pragma("unroll") for (int k = 0; k < 2; ++k) \
;         acc[ai][bj][m][n] = __builtin_amdgcn_mfma_f32_16x16x32_bf16(Bt[n][k], At[m][k], acc[ai][bj][m][n], 0, 0, 0); __builtin_amdgcn_s_setprio(0); } while (0)
; #define PG8_WAIT_V(n) asm volatile("s_waitcnt vmcnt(" #n ")" ::: "memory")
; #define PG8_WAIT_L(n) asm volatile("s_waitcnt lgkmcnt(" #n ")" ::: "memory")
; #define PG8_BAR __builtin_amdgcn_s_barrier()
; #define PG8_SCHED __builtin_amdgcn_sched_barrier(0)
; template <class Epi, class Sched, bool ALIGN_EPI = false, bool SP2 = false>
; __device__ __forceinline__ void gemm_phase(PG8_LAS unsigned char* lds, const Gemm g, const Sched& S, const Epi& E) {
;     ...
;             PG8_WAIT_V(8); PG8_WAIT_L(0); PG8_BAR; PG8_MMA(1, 0, At, B0); PG8_MMA(1, 1, At, B1); PG8_BAR; PG8_SCHED;
;             PG8_LDB(B0, 1, 0); PG8_LDB(B1, 1, 1); PG8_SCHED; PG8_LDA(At, 1, 0); PG8_STAGE(PG8_SA(0, 1), a2 + hstep, voffA);
;             PG8_WAIT_V(8); PG8_WAIT_L(0); PG8_BAR; PG8_MMA(0, 0, At, B0); PG8_MMA(0, 1, At, B1); PG8_BAR; PG8_SCHED;
	s_setprio 1
	v_mfma_f32_16x16x32_bf16 v[60:63], v[130:133], v[162:165], v[60:63]
	v_mfma_f32_16x16x32_bf16 v[56:59], v[138:141], v[162:165], v[56:59]
	v_mfma_f32_16x16x32_bf16 v[48:51], v[130:133], v[170:173], v[48:51]
	v_mfma_f32_16x16x32_bf16 v[40:43], v[138:141], v[170:173], v[40:43]
	v_mfma_f32_16x16x32_bf16 v[32:35], v[130:133], v[208:211], v[32:35]
	v_mfma_f32_16x16x32_bf16 v[24:27], v[138:141], v[208:211], v[24:27]
	v_mfma_f32_16x16x32_bf16 v[16:19], v[130:133], v[232:235], v[16:19]
	v_mfma_f32_16x16x32_bf16 v[8:11], v[138:141], v[232:235], v[8:11]
	v_mfma_f32_16x16x32_bf16 v[60:63], v[134:137], v[166:169], v[60:63]
	v_mfma_f32_16x16x32_bf16 v[56:59], v[142:145], v[166:169], v[56:59]
	v_mfma_f32_16x16x32_bf16 v[48:51], v[134:137], v[174:177], v[48:51]
	v_mfma_f32_16x16x32_bf16 v[40:43], v[142:145], v[174:177], v[40:43]
	v_mfma_f32_16x16x32_bf16 v[32:35], v[134:137], v[212:215], v[32:35]
	v_mfma_f32_16x16x32_bf16 v[24:27], v[142:145], v[212:215], v[24:27]
	v_mfma_f32_16x16x32_bf16 v[16:19], v[134:137], v[242:245], v[16:19]
	v_mfma_f32_16x16x32_bf16 v[8:11], v[142:145], v[242:245], v[8:11]
	v_mfma_f32_16x16x32_bf16 v[52:55], v[146:149], v[162:165], v[52:55]
	v_mfma_f32_16x16x32_bf16 v[44:47], v[154:157], v[162:165], v[44:47]
	v_mfma_f32_16x16x32_bf16 v[36:39], v[146:149], v[170:173], v[36:39]
	v_mfma_f32_16x16x32_bf16 v[28:31], v[154:157], v[170:173], v[28:31]
	v_mfma_f32_16x16x32_bf16 v[20:23], v[146:149], v[208:211], v[20:23]
	v_mfma_f32_16x16x32_bf16 v[12:15], v[154:157], v[208:211], v[12:15]
	v_mfma_f32_16x16x32_bf16 v[4:7], v[146:149], v[232:235], v[4:7]
	v_mfma_f32_16x16x32_bf16 v[0:3], v[154:157], v[232:235], v[0:3]
	v_mfma_f32_16x16x32_bf16 v[52:55], v[150:153], v[166:169], v[52:55]
	v_mfma_f32_16x16x32_bf16 v[44:47], v[158:161], v[166:169], v[44:47]
	v_mfma_f32_16x16x32_bf16 v[36:39], v[150:153], v[174:177], v[36:39]
	v_mfma_f32_16x16x32_bf16 v[28:31], v[158:161], v[174:177], v[28:31]
	v_mfma_f32_16x16x32_bf16 v[20:23], v[150:153], v[212:215], v[20:23]
	v_mfma_f32_16x16x32_bf16 v[12:15], v[158:161], v[212:215], v[12:15]
	v_mfma_f32_16x16x32_bf16 v[4:7], v[150:153], v[242:245], v[4:7]
	v_mfma_f32_16x16x32_bf16 v[0:3], v[158:161], v[242:245], v[0:3]
	s_setprio 0
	s_barrier
	s_add_i32 s96, 0, 0x18000
	s_add_i32 s97, 0, 0x1c000
	v_add_u32_e32 v142, s96, v193
	v_add_u32_e32 v158, s97, v193
	ds_read_b128 v[130:133], v142
	ds_read_b128 v[134:137], v142 offset:1024
	ds_read_b128 v[138:141], v142 offset:2048
	ds_read_b128 v[142:145], v142 offset:3072
	ds_read_b128 v[146:149], v158
	ds_read_b128 v[150:153], v158 offset:1024
	ds_read_b128 v[154:157], v158 offset:2048
	ds_read_b128 v[158:161], v158 offset:3072
	s_add_u32 s0, s0, s28
	s_addc_u32 s1, s1, 0
	s_mov_b32 m0, s9
	v_lshl_add_u64 v[250:251], s[0:1], 0, v[182:183]
	ds_read_b128 v[162:165], v207 offset:32768
	ds_read_b128 v[166:169], v207 offset:33792
	ds_read_b128 v[170:173], v207 offset:34816
	ds_read_b128 v[174:177], v207 offset:35840
	ds_read_b128 v[208:211], v207 offset:36864
	ds_read_b128 v[212:215], v207 offset:37888
	ds_read_b128 v[232:235], v207 offset:38912
	ds_read_b128 v[242:245], v207 offset:39936
	global_load_lds_dwordx4 v[250:251], off
	v_lshl_add_u64 v[250:251], s[0:1], 0, v[180:181]
	s_mov_b32 m0, s33
	s_nop 0
	global_load_lds_dwordx4 v[250:251], off
	s_waitcnt vmcnt(8)
	s_waitcnt lgkmcnt(0)
	s_barrier
	s_setprio 1
	v_mfma_f32_16x16x32_bf16 v[126:129], v[130:133], v[162:165], v[126:129]
	v_mfma_f32_16x16x32_bf16 v[122:125], v[138:141], v[162:165], v[122:125]
	v_mfma_f32_16x16x32_bf16 v[114:117], v[130:133], v[170:173], v[114:117]
	v_mfma_f32_16x16x32_bf16 v[106:109], v[138:141], v[170:173], v[106:109]
	v_mfma_f32_16x16x32_bf16 v[98:101], v[130:133], v[208:211], v[98:101]
	v_mfma_f32_16x16x32_bf16 v[88:91], v[138:141], v[208:211], v[88:91]
	v_mfma_f32_16x16x32_bf16 v[80:83], v[130:133], v[232:235], v[80:83]
	v_mfma_f32_16x16x32_bf16 v[72:75], v[138:141], v[232:235], v[72:75]
	v_mfma_f32_16x16x32_bf16 v[126:129], v[134:137], v[166:169], v[126:129]
	v_mfma_f32_16x16x32_bf16 v[122:125], v[142:145], v[166:169], v[122:125]
	v_mfma_f32_16x16x32_bf16 v[114:117], v[134:137], v[174:177], v[114:117]
	v_mfma_f32_16x16x32_bf16 v[106:109], v[142:145], v[174:177], v[106:109]
	v_mfma_f32_16x16x32_bf16 v[98:101], v[134:137], v[212:215], v[98:101]
	v_mfma_f32_16x16x32_bf16 v[88:91], v[142:145], v[212:215], v[88:91]
	v_mfma_f32_16x16x32_bf16 v[80:83], v[134:137], v[242:245], v[80:83]
	v_mfma_f32_16x16x32_bf16 v[72:75], v[142:145], v[242:245], v[72:75]
	v_mfma_f32_16x16x32_bf16 v[118:121], v[146:149], v[162:165], v[118:121]
	v_mfma_f32_16x16x32_bf16 v[110:113], v[154:157], v[162:165], v[110:113]
	v_mfma_f32_16x16x32_bf16 v[102:105], v[146:149], v[170:173], v[102:105]
	v_mfma_f32_16x16x32_bf16 v[92:95], v[154:157], v[170:173], v[92:95]
	v_mfma_f32_16x16x32_bf16 v[84:87], v[146:149], v[208:211], v[84:87]
	v_mfma_f32_16x16x32_bf16 v[76:79], v[154:157], v[208:211], v[76:79]
	v_mfma_f32_16x16x32_bf16 v[68:71], v[146:149], v[232:235], v[68:71]
	v_mfma_f32_16x16x32_bf16 v[64:67], v[154:157], v[232:235], v[64:67]
	v_mfma_f32_16x16x32_bf16 v[118:121], v[150:153], v[166:169], v[118:121]
	v_mfma_f32_16x16x32_bf16 v[110:113], v[158:161], v[166:169], v[110:113]
	v_mfma_f32_16x16x32_bf16 v[102:105], v[150:153], v[174:177], v[102:105]
	v_mfma_f32_16x16x32_bf16 v[92:95], v[158:161], v[174:177], v[92:95]
	v_mfma_f32_16x16x32_bf16 v[84:87], v[150:153], v[212:215], v[84:87]
	v_mfma_f32_16x16x32_bf16 v[76:79], v[158:161], v[212:215], v[76:79]
	v_mfma_f32_16x16x32_bf16 v[68:71], v[150:153], v[242:245], v[68:71]
	v_mfma_f32_16x16x32_bf16 v[64:67], v[158:161], v[242:245], v[64:67]
	s_setprio 0
	s_barrier
; #define PG8_STAGE(bufoff, gbase, voff) do { _Pragma("unroll") for (int _i = 0; _i < 2; ++_i) \
;         __builtin_amdgcn_global_load_lds((const unsigned*)((const char*)(gbase) + (voff)[_i]), (PG8_LAS unsigned*)(lds + (bufoff) + ldsw + _i * 8192), 16, 0, 0); } while (0)
; #define PG8_LDA(dst, b, h) do { _Pragma("unroll") for (int m = 0; m < 4; ++m) _Pragma("unroll") for (int k = 0; k < 2; ++k) dst[m][k] = *(const PG8_LAS bf16x8*)(lds + PG8_SA(b, h) + aoff + m * 2048 + k * 1024); } while (0)
; #define PG8_MMA(ai, bj, At, Bt) do { __builtin_amdgcn_s_setprio(1); _Pragma("unroll") for (int m = 0; m < 4; ++m) _Pragma("unroll") for (int n = 0; n < 2; ++n) _Pragma("unroll") for (int k = 0; k < 2; ++k) \
;         acc[ai][bj][m][n] = __builtin_amdgcn_mfma_f32_16x16x32_bf16(Bt[n][k], At[m][k], acc[ai][bj][m][n], 0, 0, 0); __builtin_amdgcn_s_setprio(0); } while (0)
; #define PG8_WAIT_V(n) asm volatile("s_waitcnt vmcnt(" #n ")" ::: "memory")
; #define PG8_WAIT_L(n) asm volatile("s_waitcnt lgkmcnt(" #n ")" ::: "memory")
; #define PG8_BAR __builtin_amdgcn_s_barrier()
; #define PG8_SCHED __builtin_amdgcn_sched_barrier(0)
; template <class Epi, class Sched, bool ALIGN_EPI = false, bool SP2 = false>
; __device__ __forceinline__ void gemm_phase(PG8_LAS unsigned char* lds, const Gemm g, const Sched& S, const Epi& E) {
;     ...
;             PG8_LDA(At, 1, 1); PG8_STAGE(PG8_SB(1, 0), b3, voffB); PG8_STAGE(PG8_SB(1, 1), b3 + hstep, voffB); PG8_STAGE(PG8_SA(1, 0), a3, voffA);
;             PG8_WAIT_V(8); PG8_WAIT_L(0); PG8_BAR; PG8_MMA(1, 0, At, B0); PG8_MMA(1, 1, At, B1); PG8_BAR; PG8_SCHED;
	s_add_i32 s0, s96, s4
	v_lshl_add_u64 v[202:203], v[202:203], 0, s[20:21]
	s_mov_b32 m0, s0
	ds_read_b128 v[162:165], v207 offset:49152
	ds_read_b128 v[166:169], v207 offset:50176
	ds_read_b128 v[170:173], v207 offset:51200
	ds_read_b128 v[174:177], v207 offset:52224
	ds_read_b128 v[208:211], v207 offset:53248
	ds_read_b128 v[212:215], v207 offset:54272
	ds_read_b128 v[232:235], v207 offset:55296
	ds_read_b128 v[242:245], v207 offset:56320
	global_load_lds_dwordx4 v[202:203], off
	v_lshl_add_u64 v[202:203], v[228:229], 0, s[20:21]
	s_add_i32 m0, s0, 0x2000
	s_add_i32 s0, s97, s4
	global_load_lds_dwordx4 v[202:203], off
	v_lshl_add_u64 v[202:203], v[230:231], 0, s[20:21]
	s_mov_b32 m0, s0
	s_nop 0
	global_load_lds_dwordx4 v[202:203], off
	v_lshl_add_u64 v[202:203], v[246:247], 0, s[20:21]
	s_add_i32 m0, s0, 0x2000
	s_nop 0
	global_load_lds_dwordx4 v[202:203], off
	v_lshl_add_u64 v[202:203], v[248:249], 0, s[20:21]
	s_mov_b32 m0, s53
	s_nop 0
	global_load_lds_dwordx4 v[202:203], off
	v_lshl_add_u64 v[202:203], v[236:237], 0, s[20:21]
	s_mov_b32 m0, s93
	s_nop 0
	global_load_lds_dwordx4 v[202:203], off
	s_waitcnt vmcnt(8)
	s_waitcnt lgkmcnt(0)
	s_barrier
	s_setprio 1
	v_mfma_f32_16x16x32_bf16 v[60:63], v[130:133], v[162:165], v[60:63]
	v_mfma_f32_16x16x32_bf16 v[56:59], v[138:141], v[162:165], v[56:59]
	v_mfma_f32_16x16x32_bf16 v[48:51], v[130:133], v[170:173], v[48:51]
	v_mfma_f32_16x16x32_bf16 v[40:43], v[138:141], v[170:173], v[40:43]
	v_mfma_f32_16x16x32_bf16 v[32:35], v[130:133], v[208:211], v[32:35]
	v_mfma_f32_16x16x32_bf16 v[24:27], v[138:141], v[208:211], v[24:27]
	v_mfma_f32_16x16x32_bf16 v[16:19], v[130:133], v[232:235], v[16:19]
	v_mfma_f32_16x16x32_bf16 v[8:11], v[138:141], v[232:235], v[8:11]
	v_mfma_f32_16x16x32_bf16 v[60:63], v[134:137], v[166:169], v[60:63]
	v_mfma_f32_16x16x32_bf16 v[56:59], v[142:145], v[166:169], v[56:59]
	v_mfma_f32_16x16x32_bf16 v[48:51], v[134:137], v[174:177], v[48:51]
	v_mfma_f32_16x16x32_bf16 v[40:43], v[142:145], v[174:177], v[40:43]
	v_mfma_f32_16x16x32_bf16 v[32:35], v[134:137], v[212:215], v[32:35]
	v_mfma_f32_16x16x32_bf16 v[24:27], v[142:145], v[212:215], v[24:27]
	v_mfma_f32_16x16x32_bf16 v[16:19], v[134:137], v[242:245], v[16:19]
	v_mfma_f32_16x16x32_bf16 v[8:11], v[142:145], v[242:245], v[8:11]
	v_mfma_f32_16x16x32_bf16 v[52:55], v[146:149], v[162:165], v[52:55]
	v_mfma_f32_16x16x32_bf16 v[44:47], v[154:157], v[162:165], v[44:47]
	v_mfma_f32_16x16x32_bf16 v[36:39], v[146:149], v[170:173], v[36:39]
	v_mfma_f32_16x16x32_bf16 v[28:31], v[154:157], v[170:173], v[28:31]
	v_mfma_f32_16x16x32_bf16 v[20:23], v[146:149], v[208:211], v[20:23]
	v_mfma_f32_16x16x32_bf16 v[12:15], v[154:157], v[208:211], v[12:15]
	v_mfma_f32_16x16x32_bf16 v[4:7], v[146:149], v[232:235], v[4:7]
	v_mfma_f32_16x16x32_bf16 v[0:3], v[154:157], v[232:235], v[0:3]
	v_mfma_f32_16x16x32_bf16 v[52:55], v[150:153], v[166:169], v[52:55]
	v_mfma_f32_16x16x32_bf16 v[44:47], v[158:161], v[166:169], v[44:47]
	v_mfma_f32_16x16x32_bf16 v[36:39], v[150:153], v[174:177], v[36:39]
	v_mfma_f32_16x16x32_bf16 v[28:31], v[158:161], v[174:177], v[28:31]
	v_mfma_f32_16x16x32_bf16 v[20:23], v[150:153], v[212:215], v[20:23]
	v_mfma_f32_16x16x32_bf16 v[12:15], v[158:161], v[212:215], v[12:15]
	v_mfma_f32_16x16x32_bf16 v[4:7], v[150:153], v[242:245], v[4:7]
	v_mfma_f32_16x16x32_bf16 v[0:3], v[158:161], v[242:245], v[0:3]
	s_setprio 0
	s_barrier
	s_add_u32 s45, s45, 0x100
	s_addc_u32 s94, s94, 0
	s_add_u32 s40, s40, 0x100
	s_addc_u32 s41, s41, 0
	s_cmp_ge_u32 s95, s58
	s_mov_b32 s0, s95
	s_cbranch_scc0 .LBB0_510
	s_and_b64 vcc, exec, s[82:83]
	s_cbranch_vccz .LBB0_513
	s_barrier
